# one static s_setprio 1 for waves 4-7 (younger half) during the differential-attention tile loop
# speedup vs baseline: 1.1039x; 1.0015x over previous
.LBB0_574:
	s_add_i32 s11, s11, s17
	v_lshlrev_b32_e32 v182, 2, v0
	v_lshrrev_b32_e32 v3, 2, v1
	s_mul_hi_u32 s13, s11, 0x1200
	s_mulk_i32 s11, 0x1200
	v_readlane_b32 s16, v252, 52
	v_and_or_b32 v3, v3, 3, v182
	v_readlane_b32 s17, v252, 53
	s_add_u32 s12, s16, s11
	v_lshlrev_b32_e32 v4, 1, v1
	v_lshlrev_b32_e32 v184, 6, v3
	s_addc_u32 s13, s17, s13
	v_add_u32_e32 v3, 0x4000, v183
	v_and_b32_e32 v185, 32, v4
	v_lshl_add_u64 v[4:5], v[126:127], 1, s[12:13]
	s_mov_b64 s[16:17], 0xe00
	v_readfirstlane_b32 s11, v3
	v_add_u32_e32 v3, 0x6000, v183
	v_lshl_add_u64 v[4:5], v[4:5], 0, s[16:17]
	s_mov_b32 m0, s11
	v_readfirstlane_b32 s11, v3
	global_load_lds_dwordx4 v[4:5], off
	v_lshl_add_u64 v[4:5], v[124:125], 1, s[12:13]
	s_mov_b32 m0, s11
	v_lshlrev_b32_e32 v186, 7, v2
	global_load_lds_dwordx4 v[4:5], off
	v_lshrrev_b32_e32 v2, 1, v1
	v_bfe_u32 v1, v1, 1, 3
	v_bitop3_b32 v2, v0, v2, 7 bitop3:0x78
	v_lshlrev_b32_e32 v187, 4, v2
	v_bitop3_b32 v2, v0, v1, 2 bitop3:0x36
	s_waitcnt vmcnt(2)
	s_barrier
	v_lshlrev_b32_e32 v188, 4, v2
	v_bitop3_b32 v2, v0, v1, 4 bitop3:0x36
	v_bitop3_b32 v0, v0, v1, 6 bitop3:0x36
	v_lshlrev_b32_e32 v190, 4, v0
	v_mov_b32_e32 v0, 0
	v_ashrrev_i32_e32 v123, 31, v122
	s_or_b32 s9, s9, 0x2080
	s_or_b32 s16, s10, 0x80
	v_lshlrev_b32_e32 v189, 4, v2
	s_lshl_b32 s17, s15, 6
	s_mov_b32 s18, 0
	v_mov_b32_e32 v1, v0
	v_mov_b32_e32 v2, v0
	v_mov_b32_e32 v3, v0
	v_mov_b32_e32 v4, v0
	v_mov_b32_e32 v5, v0
	v_mov_b32_e32 v6, v0
	v_mov_b32_e32 v7, v0
	v_mov_b32_e32 v8, v0
	v_mov_b32_e32 v9, v0
	v_mov_b32_e32 v10, v0
	v_mov_b32_e32 v11, v0
	v_mov_b32_e32 v12, v0
	v_mov_b32_e32 v13, v0
	v_mov_b32_e32 v14, v0
	v_mov_b32_e32 v15, v0
	v_mov_b32_e32 v32, v0
	v_mov_b32_e32 v33, v0
	v_mov_b32_e32 v34, v0
	v_mov_b32_e32 v35, v0
	v_mov_b32_e32 v36, v0
	v_mov_b32_e32 v37, v0
	v_mov_b32_e32 v38, v0
	v_mov_b32_e32 v39, v0
	v_mov_b32_e32 v40, v0
	v_mov_b32_e32 v41, v0
	v_mov_b32_e32 v42, v0
	v_mov_b32_e32 v43, v0
	v_mov_b32_e32 v44, v0
	v_mov_b32_e32 v45, v0
	v_mov_b32_e32 v46, v0
	v_mov_b32_e32 v47, v0
	v_mov_b32_e32 v16, v0
	v_mov_b32_e32 v17, v0
	v_mov_b32_e32 v18, v0
	v_mov_b32_e32 v19, v0
	v_mov_b32_e32 v20, v0
	v_mov_b32_e32 v21, v0
	v_mov_b32_e32 v22, v0
	v_mov_b32_e32 v23, v0
	v_mov_b32_e32 v24, v0
	v_mov_b32_e32 v25, v0
	v_mov_b32_e32 v26, v0
	v_mov_b32_e32 v27, v0
	v_mov_b32_e32 v28, v0
	v_mov_b32_e32 v29, v0
	v_mov_b32_e32 v30, v0
	v_mov_b32_e32 v31, v0
	v_mov_b32_e32 v48, v0
	v_mov_b32_e32 v49, v0
	v_mov_b32_e32 v50, v0
	v_mov_b32_e32 v51, v0
	v_mov_b32_e32 v52, v0
	v_mov_b32_e32 v53, v0
	v_mov_b32_e32 v54, v0
	v_mov_b32_e32 v55, v0
	v_mov_b32_e32 v56, v0
	v_mov_b32_e32 v57, v0
	v_mov_b32_e32 v58, v0
	v_mov_b32_e32 v59, v0
	v_mov_b32_e32 v60, v0
	v_mov_b32_e32 v61, v0
	v_mov_b32_e32 v62, v0
	v_mov_b32_e32 v63, v0
	v_mov_b32_e32 v128, v0
	v_mov_b32_e32 v129, v0
	s_waitcnt vmcnt(0)
	v_add_u32_e32 v200, v186, v187
	v_add_u32_e32 v201, v186, v188
	v_add_u32_e32 v202, v186, v189
	v_add_u32_e32 v203, v186, v190
	v_add3_u32 v204, v184, v160, v185
	v_readfirstlane_b32 s18, v183
	v_readlane_b32 s22, v252, 52
	v_readlane_b32 s23, v252, 53
	v_mov_b32_e32 v130, 0
	v_mov_b32_e32 v131, 0
	s_mov_b64 s[12:13], 0xe00
	v_lshl_add_u64 v[206:207], v[126:127], 1, s[22:23]
	v_lshl_add_u64 v[210:211], v[124:125], 1, s[22:23]
	v_lshl_add_u64 v[206:207], v[206:207], 0, s[12:13]
	s_cmpk_lt_u32 s15, 0x7e
	s_cselect_b32 s12, s16, s9
	s_add_i32 s12, s12, s17
	s_mul_i32 s12, s12, 0x1200
	s_mov_b32 s13, 0
	s_add_i32 s10, s18, 0x8000
	s_mov_b32 m0, s10
	v_lshl_add_u64 v[222:223], v[206:207], 0, s[12:13]
	global_load_lds_dwordx4 v[222:223], off
	s_add_i32 m0, s10, 0x2000
	v_lshl_add_u64 v[222:223], v[210:211], 0, s[12:13]
	global_load_lds_dwordx4 v[222:223], off
	ds_read_b128 v[112:115], v200
	ds_read_b128 v[116:119], v200 offset:4096
	ds_read_b128 v[148:151], v201
	ds_read_b128 v[152:155], v201 offset:4096
	ds_read_b128 v[156:159], v202
	ds_read_b128 v[162:165], v202 offset:4096
	ds_read_b128 v[174:177], v203
	ds_read_b128 v[178:181], v203 offset:4096
	s_waitcnt lgkmcnt(0)
	v_mfma_f32_32x32x16_bf16 v[64:79], v[112:115], v[80:83], 0
	v_mfma_f32_32x32x16_bf16 v[96:111], v[116:119], v[80:83], 0
	v_mfma_f32_32x32x16_bf16 v[64:79], v[148:151], v[84:87], v[64:79]
	v_mfma_f32_32x32x16_bf16 v[96:111], v[152:155], v[84:87], v[96:111]
	v_mfma_f32_32x32x16_bf16 v[132:147], v[156:159], v[88:91], 0
	v_mfma_f32_32x32x16_bf16 v[184:199], v[162:165], v[88:91], 0
	v_mfma_f32_32x32x16_bf16 v[132:147], v[174:177], v[92:95], v[132:147]
	v_mfma_f32_32x32x16_bf16 v[184:199], v[178:181], v[92:95], v[184:199]
	s_nop 7
	v_exp_f32_e32 v64, v64
	v_exp_f32_e32 v65, v65
	v_exp_f32_e32 v66, v66
	v_exp_f32_e32 v67, v67
	v_exp_f32_e32 v68, v68
	v_exp_f32_e32 v69, v69
	v_exp_f32_e32 v70, v70
	v_exp_f32_e32 v71, v71
	v_exp_f32_e32 v72, v72
	v_exp_f32_e32 v73, v73
	v_exp_f32_e32 v74, v74
	v_exp_f32_e32 v75, v75
	v_exp_f32_e32 v76, v76
	v_exp_f32_e32 v77, v77
	v_exp_f32_e32 v78, v78
	v_exp_f32_e32 v79, v79
	v_add_f32_e32 v128, v64, v128
	v_add_f32_e32 v130, v65, v130
	v_add_f32_e32 v128, v66, v128
	v_add_f32_e32 v130, v67, v130
	v_add_f32_e32 v128, v68, v128
	v_add_f32_e32 v130, v69, v130
	v_add_f32_e32 v128, v70, v128
	v_add_f32_e32 v130, v71, v130
	v_add_f32_e32 v128, v72, v128
	v_add_f32_e32 v130, v73, v130
	v_add_f32_e32 v128, v74, v128
	v_add_f32_e32 v130, v75, v130
	v_add_f32_e32 v128, v76, v128
	v_add_f32_e32 v130, v77, v130
	v_add_f32_e32 v128, v78, v128
	v_add_f32_e32 v130, v79, v130
	v_cvt_pk_bf16_f32 v64, v64, v65
	v_cvt_pk_bf16_f32 v65, v66, v67
	v_cvt_pk_bf16_f32 v66, v68, v69
	v_cvt_pk_bf16_f32 v67, v70, v71
	v_cvt_pk_bf16_f32 v68, v72, v73
	v_cvt_pk_bf16_f32 v69, v74, v75
	v_cvt_pk_bf16_f32 v70, v76, v77
	v_cvt_pk_bf16_f32 v71, v78, v79
	v_exp_f32_e32 v96, v96
	v_exp_f32_e32 v97, v97
	v_exp_f32_e32 v98, v98
	v_exp_f32_e32 v99, v99
	v_exp_f32_e32 v100, v100
	v_exp_f32_e32 v101, v101
	v_exp_f32_e32 v102, v102
	v_exp_f32_e32 v103, v103
	v_exp_f32_e32 v104, v104
	v_exp_f32_e32 v105, v105
	v_exp_f32_e32 v106, v106
	v_exp_f32_e32 v107, v107
	v_exp_f32_e32 v108, v108
	v_exp_f32_e32 v109, v109
	v_exp_f32_e32 v110, v110
	v_exp_f32_e32 v111, v111
	v_add_f32_e32 v128, v96, v128
	v_add_f32_e32 v130, v97, v130
	v_add_f32_e32 v128, v98, v128
	v_add_f32_e32 v130, v99, v130
	v_add_f32_e32 v128, v100, v128
	v_add_f32_e32 v130, v101, v130
	v_add_f32_e32 v128, v102, v128
	v_add_f32_e32 v130, v103, v130
	v_add_f32_e32 v128, v104, v128
	v_add_f32_e32 v130, v105, v130
	v_add_f32_e32 v128, v106, v128
	v_add_f32_e32 v130, v107, v130
	v_add_f32_e32 v128, v108, v128
	v_add_f32_e32 v130, v109, v130
	v_add_f32_e32 v128, v110, v128
	v_add_f32_e32 v130, v111, v130
	v_cvt_pk_bf16_f32 v96, v96, v97
	v_cvt_pk_bf16_f32 v97, v98, v99
	v_cvt_pk_bf16_f32 v98, v100, v101
	v_cvt_pk_bf16_f32 v99, v102, v103
	v_cvt_pk_bf16_f32 v100, v104, v105
	v_cvt_pk_bf16_f32 v101, v106, v107
	v_cvt_pk_bf16_f32 v102, v108, v109
	v_cvt_pk_bf16_f32 v103, v110, v111
	s_barrier
	v_readlane_b32 s10, v251, 44
	s_cmpk_lt_u32 s10, 0x100
	s_cbranch_scc1 .Ldiff_noprio
	s_setprio 1
.Ldiff_noprio:
.Ldiff_loop:
	s_cmpk_lt_u32 s15, 0x81
	s_cbranch_scc0 .Ldiff_nodma
	s_cmpk_lt_u32 s15, 0x7d
	s_cselect_b32 s12, s16, s9
	s_add_i32 s12, s12, s17
	s_add_i32 s12, s12, 64
	s_mul_i32 s12, s12, 0x1200
	s_mov_b32 s13, 0
	s_add_i32 s10, s15, 3
	s_and_b32 s10, s10, 3
	s_lshl_b32 s10, s10, 14
	s_add_i32 s10, s10, s18
	s_mov_b32 m0, s10
	v_lshl_add_u64 v[222:223], v[206:207], 0, s[12:13]
	global_load_lds_dwordx4 v[222:223], off
	s_add_i32 m0, s10, 0x2000
	v_lshl_add_u64 v[222:223], v[210:211], 0, s[12:13]
	global_load_lds_dwordx4 v[222:223], off

.Ldiff_w1:
	s_barrier
	s_add_i32 s15, s15, 1
	s_add_i32 s17, s17, 64
	s_cmpk_lt_u32 s15, 0x83
	s_cbranch_scc1 .Ldiff_loop
	s_and_b32 s19, s15, 3
	s_lshl_b32 s19, s19, 14
	v_add_u32_e32 v221, s19, v204
	ds_read_b64_tr_b16 v[156:157], v221 offset:8192
	ds_read_b64_tr_b16 v[158:159], v221 offset:9216
	ds_read_b64_tr_b16 v[162:163], v221 offset:8704
	ds_read_b64_tr_b16 v[164:165], v221 offset:9728
	ds_read_b64_tr_b16 v[174:175], v221 offset:10240
	ds_read_b64_tr_b16 v[176:177], v221 offset:11264
	v_exp_f32_e32 v132, v132
	v_exp_f32_e32 v133, v133
	v_exp_f32_e32 v134, v134
	v_exp_f32_e32 v135, v135
	s_waitcnt lgkmcnt(4)
	v_mfma_f32_32x32x16_bf16 v[32:47], v[156:159], v[64:67], v[32:47]
	ds_read_b64_tr_b16 v[178:179], v221 offset:10752
	ds_read_b64_tr_b16 v[180:181], v221 offset:11776
	v_exp_f32_e32 v136, v136
	v_exp_f32_e32 v137, v137
	v_exp_f32_e32 v138, v138
	v_exp_f32_e32 v139, v139
	v_exp_f32_e32 v140, v140
	v_exp_f32_e32 v141, v141
	v_exp_f32_e32 v142, v142
	v_exp_f32_e32 v143, v143
	v_exp_f32_e32 v144, v144
	v_exp_f32_e32 v145, v145
	s_waitcnt lgkmcnt(4)
	v_mfma_f32_32x32x16_bf16 v[0:15], v[162:165], v[64:67], v[0:15]
	ds_read_b64_tr_b16 v[156:157], v221 offset:12288
	ds_read_b64_tr_b16 v[158:159], v221 offset:13312
	v_exp_f32_e32 v146, v146
	v_exp_f32_e32 v147, v147
	v_add_f32_e32 v129, v132, v129
	v_add_f32_e32 v131, v133, v131
	v_add_f32_e32 v129, v134, v129
	v_add_f32_e32 v131, v135, v131
	v_add_f32_e32 v129, v136, v129
	v_add_f32_e32 v131, v137, v131
	v_add_f32_e32 v129, v138, v129
	v_add_f32_e32 v131, v139, v131
	v_add_f32_e32 v129, v140, v129
	s_waitcnt lgkmcnt(4)
	v_mfma_f32_32x32x16_bf16 v[32:47], v[174:177], v[68:71], v[32:47]
	ds_read_b64_tr_b16 v[162:163], v221 offset:12800
	ds_read_b64_tr_b16 v[164:165], v221 offset:13824
	v_add_f32_e32 v131, v141, v131
	v_add_f32_e32 v129, v142, v129
	v_add_f32_e32 v131, v143, v131
	v_add_f32_e32 v129, v144, v129
	v_add_f32_e32 v131, v145, v131
	v_add_f32_e32 v129, v146, v129
	v_add_f32_e32 v131, v147, v131
	v_cvt_pk_bf16_f32 v132, v132, v133
	v_cvt_pk_bf16_f32 v133, v134, v135
	v_cvt_pk_bf16_f32 v134, v136, v137
	s_waitcnt lgkmcnt(4)
	v_mfma_f32_32x32x16_bf16 v[0:15], v[178:181], v[68:71], v[0:15]
	ds_read_b64_tr_b16 v[174:175], v221 offset:14336
	ds_read_b64_tr_b16 v[176:177], v221 offset:15360
	v_cvt_pk_bf16_f32 v135, v138, v139
	v_cvt_pk_bf16_f32 v136, v140, v141
	v_cvt_pk_bf16_f32 v137, v142, v143
	v_cvt_pk_bf16_f32 v138, v144, v145
	v_cvt_pk_bf16_f32 v139, v146, v147
	v_exp_f32_e32 v184, v184
	v_exp_f32_e32 v185, v185
	v_exp_f32_e32 v186, v186
	v_exp_f32_e32 v187, v187
	v_exp_f32_e32 v188, v188
	s_waitcnt lgkmcnt(4)
	v_mfma_f32_32x32x16_bf16 v[32:47], v[156:159], v[96:99], v[32:47]
	ds_read_b64_tr_b16 v[178:179], v221 offset:14848
	ds_read_b64_tr_b16 v[180:181], v221 offset:15872
	v_exp_f32_e32 v189, v189
	v_exp_f32_e32 v190, v190
	v_exp_f32_e32 v191, v191
	v_exp_f32_e32 v192, v192
	v_exp_f32_e32 v193, v193
	v_exp_f32_e32 v194, v194
	v_exp_f32_e32 v195, v195
	v_exp_f32_e32 v196, v196
	v_exp_f32_e32 v197, v197
	v_exp_f32_e32 v198, v198
	s_waitcnt lgkmcnt(4)
	v_mfma_f32_32x32x16_bf16 v[0:15], v[162:165], v[96:99], v[0:15]
	v_exp_f32_e32 v199, v199
	v_add_f32_e32 v129, v184, v129
	v_add_f32_e32 v131, v185, v131
	v_add_f32_e32 v129, v186, v129
	v_add_f32_e32 v131, v187, v131
	v_add_f32_e32 v129, v188, v129
	v_add_f32_e32 v131, v189, v131
	v_add_f32_e32 v129, v190, v129
	v_add_f32_e32 v131, v191, v131
	v_add_f32_e32 v129, v192, v129
	v_add_f32_e32 v131, v193, v131
	s_waitcnt lgkmcnt(2)
	v_mfma_f32_32x32x16_bf16 v[32:47], v[174:177], v[100:103], v[32:47]
	v_add_f32_e32 v129, v194, v129
	v_add_f32_e32 v131, v195, v131
	v_add_f32_e32 v129, v196, v129
	v_add_f32_e32 v131, v197, v131
	v_add_f32_e32 v129, v198, v129
	v_add_f32_e32 v131, v199, v131
	v_cvt_pk_bf16_f32 v184, v184, v185
	v_cvt_pk_bf16_f32 v185, v186, v187
	v_cvt_pk_bf16_f32 v186, v188, v189
	v_cvt_pk_bf16_f32 v187, v190, v191
	s_waitcnt lgkmcnt(0)
	v_mfma_f32_32x32x16_bf16 v[0:15], v[178:181], v[100:103], v[0:15]
	v_cvt_pk_bf16_f32 v188, v192, v193
	v_cvt_pk_bf16_f32 v189, v194, v195
	v_cvt_pk_bf16_f32 v190, v196, v197
	v_cvt_pk_bf16_f32 v191, v198, v199
	ds_read_b64_tr_b16 v[156:157], v221 offset:8192
	ds_read_b64_tr_b16 v[158:159], v221 offset:9216
	ds_read_b64_tr_b16 v[162:163], v221 offset:8704
	ds_read_b64_tr_b16 v[164:165], v221 offset:9728
	ds_read_b64_tr_b16 v[174:175], v221 offset:10240
	ds_read_b64_tr_b16 v[176:177], v221 offset:11264
	s_waitcnt lgkmcnt(4)
	v_mfma_f32_32x32x16_bf16 v[48:63], v[156:159], v[132:135], v[48:63]
	ds_read_b64_tr_b16 v[178:179], v221 offset:10752
	ds_read_b64_tr_b16 v[180:181], v221 offset:11776
	s_waitcnt lgkmcnt(4)
	v_mfma_f32_32x32x16_bf16 v[16:31], v[162:165], v[132:135], v[16:31]
	ds_read_b64_tr_b16 v[156:157], v221 offset:12288
	ds_read_b64_tr_b16 v[158:159], v221 offset:13312
	s_waitcnt lgkmcnt(4)
	v_mfma_f32_32x32x16_bf16 v[48:63], v[174:177], v[136:139], v[48:63]
	ds_read_b64_tr_b16 v[162:163], v221 offset:12800
	ds_read_b64_tr_b16 v[164:165], v221 offset:13824
	s_waitcnt lgkmcnt(4)
	v_mfma_f32_32x32x16_bf16 v[16:31], v[178:181], v[136:139], v[16:31]
	ds_read_b64_tr_b16 v[174:175], v221 offset:14336
	ds_read_b64_tr_b16 v[176:177], v221 offset:15360
	s_waitcnt lgkmcnt(4)
	v_mfma_f32_32x32x16_bf16 v[48:63], v[156:159], v[184:187], v[48:63]
	ds_read_b64_tr_b16 v[178:179], v221 offset:14848
	ds_read_b64_tr_b16 v[180:181], v221 offset:15872
	s_waitcnt lgkmcnt(4)
	v_mfma_f32_32x32x16_bf16 v[16:31], v[162:165], v[184:187], v[16:31]
	s_waitcnt lgkmcnt(2)
	v_mfma_f32_32x32x16_bf16 v[48:63], v[174:177], v[188:191], v[48:63]
	s_waitcnt lgkmcnt(0)
	v_mfma_f32_32x32x16_bf16 v[16:31], v[178:181], v[188:191], v[16:31]
	s_barrier
	s_setprio 0
	v_add_f32_e32 v128, v128, v130
	v_add_f32_e32 v129, v129, v131
	s_branch .LBB0_561
